# P5 layer 0: quarter-full third round split by rows over all 256 WGs (64-row sub-tiles, same K loop with 2 row fragments per wave)
# speedup vs baseline: 1.0153x; 1.0153x over previous
.Lp5_skew1:
	s_nop 7
	s_nop 1
	s_cmp_lt_u32 s20, 0x80
	v_readlane_b32 s4, v254, 55
	v_readlane_b32 s5, v254, 56
	v_readlane_b32 s2, v254, 12
	v_readlane_b32 s3, v254, 13
	s_cselect_b32 s42, s2, s4
	s_cselect_b32 s43, s3, s5
	s_and_b32 s2, s20, 0x7f
	s_lshl_b32 s2, s2, 20
	s_lshl_b32 s3, s19, 10
	s_add_i32 s2, s2, s3
	s_add_u32 s42, s42, s2
	s_addc_u32 s43, s43, 0
	s_lshr_b32 s2, s20, 3
	s_cmp_lt_u32 s20, 0x80
	s_cselect_b32 s2, s2, 16
	s_add_i32 s2, s2, s54
	s_mul_i32 s2, s2, 0x6000
	s_add_i32 s2, s2, s3
	s_add_i32 s2, s2, 0x5000
	v_readlane_b32 s4, v254, 14
	v_readlane_b32 s5, v254, 15
	s_nop 3
	s_add_u32 s44, s4, s2
	s_addc_u32 s45, s5, 0
	v_and_b32_e32 v197, 15, v222
	v_lshrrev_b32_e32 v198, 8, v222
	v_lshl_or_b32 v197, v198, 7, v197
	v_bfe_u32 v198, v222, 6, 2
	v_bfe_u32 v199, v222, 4, 2
	v_lshlrev_b32_e32 v199, 4, v199
	v_lshl_or_b32 v196, v198, 8, v199
	v_lshl_or_b32 v194, v197, 12, v196
	v_mov_b32_e32 v195, v194
	global_load_dwordx4 v[178:181], v196, s[44:45] offset:0
	global_load_dwordx4 v[182:185], v196, s[44:45] offset:64
	global_load_dwordx4 v[186:189], v196, s[44:45] offset:128
	global_load_dwordx4 v[190:193], v196, s[44:45] offset:192
	global_load_dwordx4 v[130:133], v194, s[42:43] offset:0
	global_load_dwordx4 v[134:137], v194, s[42:43] offset:64
	global_load_dwordx4 v[138:141], v194, s[42:43] offset:128
	global_load_dwordx4 v[142:145], v194, s[42:43] offset:192
	v_add_u32_e32 v194, 0x10000, v194
	global_load_dwordx4 v[146:149], v194, s[42:43] offset:0
	global_load_dwordx4 v[150:153], v194, s[42:43] offset:64
	global_load_dwordx4 v[154:157], v194, s[42:43] offset:128
	global_load_dwordx4 v[158:161], v194, s[42:43] offset:192
	v_add_u32_e32 v194, 0x10000, v194
	global_load_dwordx4 v[162:165], v194, s[42:43] offset:0
	global_load_dwordx4 v[166:169], v194, s[42:43] offset:64
	global_load_dwordx4 v[170:173], v194, s[42:43] offset:128
	global_load_dwordx4 v[174:177], v194, s[42:43] offset:192
	v_add_u32_e32 v194, 0x10000, v194
	s_add_i32 s2, s18, s95
	s_cmp_lt_i32 s2, 0x200
	s_cselect_b32 s28, 1, 0
	s_cselect_b32 s18, s2, s18
	s_lshr_b32 s2, s18, 5
	s_lshl_b32 s2, s2, 3
	s_and_b32 s3, s18, 7
	s_add_i32 s20, s2, s3
	s_bfe_u32 s19, s18, 0x20003
	s_mul_i32 s2, s20, 0x160000
	s_add_u32 s36, s96, s2
	s_addc_u32 s37, s97, 0
	s_mul_i32 s2, s19, 0x160000
	s_add_u32 s38, s16, s2
	s_addc_u32 s39, s17, 0
	s_mov_b32 m0, s21
	s_nop 0
	global_load_lds_dwordx4 v1, s[36:37]
	s_add_i32 m0, s21, 0x2000
	s_add_u32 s40, s36, 0x58000
	s_addc_u32 s41, s37, 0
	global_load_lds_dwordx4 v1, s[40:41]
	s_add_i32 m0, s21, 0x4000
	s_add_u32 s40, s36, 0xb0000
	s_addc_u32 s41, s37, 0
	global_load_lds_dwordx4 v1, s[40:41]
	s_add_i32 m0, s21, 0x6000
	s_add_u32 s40, s36, 0x108000
	s_addc_u32 s41, s37, 0
	global_load_lds_dwordx4 v1, s[40:41]
	s_add_i32 m0, s21, 0x8000
	s_nop 0
	global_load_lds_dwordx4 v1, s[38:39]
	s_add_i32 m0, s21, 0xa000
	s_add_u32 s40, s38, 0x58000
	s_addc_u32 s41, s39, 0
	global_load_lds_dwordx4 v1, s[40:41]
	s_add_i32 m0, s21, 0xc000
	s_add_u32 s40, s38, 0xb0000
	s_addc_u32 s41, s39, 0
	global_load_lds_dwordx4 v1, s[40:41]
	s_add_i32 m0, s21, 0xe000
	s_add_u32 s40, s38, 0x108000
	s_addc_u32 s41, s39, 0
	global_load_lds_dwordx4 v1, s[40:41]
	s_waitcnt vmcnt(16)
	v_pk_fma_f32 v[126:127], v[126:127], v[178:179], v[130:131]
	v_pk_fma_f32 v[128:129], v[128:129], v[180:181], v[132:133]
	v_pk_fma_f32 v[122:123], v[122:123], v[182:183], v[134:135]
	v_pk_fma_f32 v[124:125], v[124:125], v[184:185], v[136:137]
	v_pk_fma_f32 v[118:119], v[118:119], v[186:187], v[138:139]
	v_pk_fma_f32 v[120:121], v[120:121], v[188:189], v[140:141]
	v_pk_fma_f32 v[114:115], v[114:115], v[190:191], v[142:143]
	v_pk_fma_f32 v[116:117], v[116:117], v[192:193], v[144:145]
	global_store_dwordx4 v195, v[126:129], s[42:43] offset:0
	global_store_dwordx4 v195, v[122:125], s[42:43] offset:64
	global_store_dwordx4 v195, v[118:121], s[42:43] offset:128
	global_store_dwordx4 v195, v[114:117], s[42:43] offset:192
	global_load_dwordx4 v[130:133], v194, s[42:43] offset:0
	global_load_dwordx4 v[134:137], v194, s[42:43] offset:64
	global_load_dwordx4 v[138:141], v194, s[42:43] offset:128
	global_load_dwordx4 v[142:145], v194, s[42:43] offset:192
	v_add_u32_e32 v194, 0x10000, v194
	s_waitcnt vmcnt(20)
	v_add_u32_e32 v195, 0x10000, v195
	v_pk_fma_f32 v[110:111], v[110:111], v[178:179], v[146:147]
	v_pk_fma_f32 v[112:113], v[112:113], v[180:181], v[148:149]
	v_pk_fma_f32 v[106:107], v[106:107], v[182:183], v[150:151]
	v_pk_fma_f32 v[108:109], v[108:109], v[184:185], v[152:153]
	v_pk_fma_f32 v[102:103], v[102:103], v[186:187], v[154:155]
	v_pk_fma_f32 v[104:105], v[104:105], v[188:189], v[156:157]
	v_pk_fma_f32 v[98:99], v[98:99], v[190:191], v[158:159]
	v_pk_fma_f32 v[100:101], v[100:101], v[192:193], v[160:161]
	global_store_dwordx4 v195, v[110:113], s[42:43] offset:0
	global_store_dwordx4 v195, v[106:109], s[42:43] offset:64
	global_store_dwordx4 v195, v[102:105], s[42:43] offset:128
	global_store_dwordx4 v195, v[98:101], s[42:43] offset:192
	global_load_dwordx4 v[146:149], v194, s[42:43] offset:0
	global_load_dwordx4 v[150:153], v194, s[42:43] offset:64
	global_load_dwordx4 v[154:157], v194, s[42:43] offset:128
	global_load_dwordx4 v[158:161], v194, s[42:43] offset:192
	v_add_u32_e32 v194, 0x10000, v194
	s_waitcnt vmcnt(24)
	v_add_u32_e32 v195, 0x10000, v195
	v_pk_fma_f32 v[94:95], v[94:95], v[178:179], v[162:163]
	v_pk_fma_f32 v[96:97], v[96:97], v[180:181], v[164:165]
	v_pk_fma_f32 v[90:91], v[90:91], v[182:183], v[166:167]
	v_pk_fma_f32 v[92:93], v[92:93], v[184:185], v[168:169]
	v_pk_fma_f32 v[86:87], v[86:87], v[186:187], v[170:171]
	v_pk_fma_f32 v[88:89], v[88:89], v[188:189], v[172:173]
	v_pk_fma_f32 v[82:83], v[82:83], v[190:191], v[174:175]
	v_pk_fma_f32 v[84:85], v[84:85], v[192:193], v[176:177]
	global_store_dwordx4 v195, v[94:97], s[42:43] offset:0
	global_store_dwordx4 v195, v[90:93], s[42:43] offset:64
	global_store_dwordx4 v195, v[86:89], s[42:43] offset:128
	global_store_dwordx4 v195, v[82:85], s[42:43] offset:192
	global_load_dwordx4 v[162:165], v194, s[42:43] offset:0
	global_load_dwordx4 v[166:169], v194, s[42:43] offset:64
	global_load_dwordx4 v[170:173], v194, s[42:43] offset:128
	global_load_dwordx4 v[174:177], v194, s[42:43] offset:192
	v_add_u32_e32 v194, 0x10000, v194
	s_waitcnt vmcnt(16)
	v_add_u32_e32 v195, 0x10000, v195
	v_pk_fma_f32 v[78:79], v[78:79], v[178:179], v[130:131]
	v_pk_fma_f32 v[80:81], v[80:81], v[180:181], v[132:133]
	v_pk_fma_f32 v[74:75], v[74:75], v[182:183], v[134:135]
	v_pk_fma_f32 v[76:77], v[76:77], v[184:185], v[136:137]
	v_pk_fma_f32 v[70:71], v[70:71], v[186:187], v[138:139]
	v_pk_fma_f32 v[72:73], v[72:73], v[188:189], v[140:141]
	v_pk_fma_f32 v[66:67], v[66:67], v[190:191], v[142:143]
	v_pk_fma_f32 v[68:69], v[68:69], v[192:193], v[144:145]
	global_store_dwordx4 v195, v[78:81], s[42:43] offset:0
	global_store_dwordx4 v195, v[74:77], s[42:43] offset:64
	global_store_dwordx4 v195, v[70:73], s[42:43] offset:128
	global_store_dwordx4 v195, v[66:69], s[42:43] offset:192
	global_load_dwordx4 v[130:133], v194, s[42:43] offset:0
	global_load_dwordx4 v[134:137], v194, s[42:43] offset:64
	global_load_dwordx4 v[138:141], v194, s[42:43] offset:128
	global_load_dwordx4 v[142:145], v194, s[42:43] offset:192
	v_add_u32_e32 v194, 0x10000, v194
	s_waitcnt vmcnt(16)
	v_add_u32_e32 v195, 0x10000, v195
	v_pk_fma_f32 v[62:63], v[62:63], v[178:179], v[146:147]
	v_pk_fma_f32 v[64:65], v[64:65], v[180:181], v[148:149]
	v_pk_fma_f32 v[58:59], v[58:59], v[182:183], v[150:151]
	v_pk_fma_f32 v[60:61], v[60:61], v[184:185], v[152:153]
	v_pk_fma_f32 v[54:55], v[54:55], v[186:187], v[154:155]
	v_pk_fma_f32 v[56:57], v[56:57], v[188:189], v[156:157]
	v_pk_fma_f32 v[50:51], v[50:51], v[190:191], v[158:159]
	v_pk_fma_f32 v[52:53], v[52:53], v[192:193], v[160:161]
	global_store_dwordx4 v195, v[62:65], s[42:43] offset:0
	global_store_dwordx4 v195, v[58:61], s[42:43] offset:64
	global_store_dwordx4 v195, v[54:57], s[42:43] offset:128
	global_store_dwordx4 v195, v[50:53], s[42:43] offset:192
	global_load_dwordx4 v[146:149], v194, s[42:43] offset:0
	global_load_dwordx4 v[150:153], v194, s[42:43] offset:64
	global_load_dwordx4 v[154:157], v194, s[42:43] offset:128
	global_load_dwordx4 v[158:161], v194, s[42:43] offset:192
	v_add_u32_e32 v194, 0x10000, v194
	s_waitcnt vmcnt(16)
	v_add_u32_e32 v195, 0x10000, v195
	v_pk_fma_f32 v[46:47], v[46:47], v[178:179], v[162:163]
	v_pk_fma_f32 v[48:49], v[48:49], v[180:181], v[164:165]
	v_pk_fma_f32 v[42:43], v[42:43], v[182:183], v[166:167]
	v_pk_fma_f32 v[44:45], v[44:45], v[184:185], v[168:169]
	v_pk_fma_f32 v[38:39], v[38:39], v[186:187], v[170:171]
	v_pk_fma_f32 v[40:41], v[40:41], v[188:189], v[172:173]
	v_pk_fma_f32 v[34:35], v[34:35], v[190:191], v[174:175]
	v_pk_fma_f32 v[36:37], v[36:37], v[192:193], v[176:177]
	global_store_dwordx4 v195, v[46:49], s[42:43] offset:0
	global_store_dwordx4 v195, v[42:45], s[42:43] offset:64
	global_store_dwordx4 v195, v[38:41], s[42:43] offset:128
	global_store_dwordx4 v195, v[34:37], s[42:43] offset:192
	s_waitcnt vmcnt(12)
	v_add_u32_e32 v195, 0x10000, v195
	v_pk_fma_f32 v[30:31], v[30:31], v[178:179], v[130:131]
	v_pk_fma_f32 v[32:33], v[32:33], v[180:181], v[132:133]
	v_pk_fma_f32 v[26:27], v[26:27], v[182:183], v[134:135]
	v_pk_fma_f32 v[28:29], v[28:29], v[184:185], v[136:137]
	v_pk_fma_f32 v[22:23], v[22:23], v[186:187], v[138:139]
	v_pk_fma_f32 v[24:25], v[24:25], v[188:189], v[140:141]
	v_pk_fma_f32 v[18:19], v[18:19], v[190:191], v[142:143]
	v_pk_fma_f32 v[20:21], v[20:21], v[192:193], v[144:145]
	global_store_dwordx4 v195, v[30:33], s[42:43] offset:0
	global_store_dwordx4 v195, v[26:29], s[42:43] offset:64
	global_store_dwordx4 v195, v[22:25], s[42:43] offset:128
	global_store_dwordx4 v195, v[18:21], s[42:43] offset:192
	s_waitcnt vmcnt(8)
	v_add_u32_e32 v195, 0x10000, v195
	v_pk_fma_f32 v[14:15], v[14:15], v[178:179], v[146:147]
	v_pk_fma_f32 v[16:17], v[16:17], v[180:181], v[148:149]
	v_pk_fma_f32 v[10:11], v[10:11], v[182:183], v[150:151]
	v_pk_fma_f32 v[12:13], v[12:13], v[184:185], v[152:153]
	v_pk_fma_f32 v[6:7], v[6:7], v[186:187], v[154:155]
	v_pk_fma_f32 v[8:9], v[8:9], v[188:189], v[156:157]
	v_pk_fma_f32 v[2:3], v[2:3], v[190:191], v[158:159]
	v_pk_fma_f32 v[4:5], v[4:5], v[192:193], v[160:161]
	global_store_dwordx4 v195, v[14:17], s[42:43] offset:0
	global_store_dwordx4 v195, v[10:13], s[42:43] offset:64
	global_store_dwordx4 v195, v[6:9], s[42:43] offset:128
	global_store_dwordx4 v195, v[2:5], s[42:43] offset:192
	s_cmp_lg_u32 s28, 0
	s_cbranch_scc1 .Lp5_cont
	s_cmp_lg_u32 s54, 0
	s_cbranch_scc1 .Lp5t_none
	s_waitcnt vmcnt(0)
	v_readlane_b32 s2, v255, 22
	s_nop 0
	s_and_b32 s4, s2, 3
	s_lshr_b32 s2, s2, 2
	s_add_i32 s18, s2, 0x200
	s_lshr_b32 s2, s18, 5
	s_lshl_b32 s2, s2, 3
	s_and_b32 s3, s18, 7
	s_add_i32 s20, s2, s3
	s_bfe_u32 s19, s18, 0x20003
	s_mul_i32 s2, s20, 0x160000
	s_add_u32 s36, s96, s2
	s_addc_u32 s37, s97, 0
	s_mul_i32 s2, s19, 0x160000
	s_add_u32 s38, s16, s2
	s_addc_u32 s39, s17, 0
	s_mul_i32 s2, s4, 0x58000
	s_add_u32 s36, s36, s2
	s_addc_u32 s37, s37, 0
	s_lshl_b32 s28, s4, 18
	v_and_b32_e32 v194, 15, v222
	v_bfe_u32 v195, v222, 4, 2
	v_bfe_u32 v196, v194, 1, 3
	v_xor_b32_e32 v195, v195, v196
	v_lshlrev_b32_e32 v195, 4, v195
	v_lshrrev_b32_e32 v196, 8, v222
	v_lshl_or_b32 v196, v196, 5, v194
	v_lshl_or_b32 v200, v196, 7, v195
	v_xor_b32_e32 v201, 64, v200
	v_bfe_u32 v196, v222, 6, 2
	v_lshl_or_b32 v196, v196, 6, v194
	v_lshl_or_b32 v202, v196, 7, v195
	v_xor_b32_e32 v203, 64, v202
	v_add_u32_e32 v204, 0x10000, v200
	v_add_u32_e32 v205, 0x10000, v201
	v_add_u32_e32 v206, 0x10000, v202
	v_add_u32_e32 v207, 0x10000, v203
	v_readfirstlane_b32 s21, v222
	s_nop 3
	s_lshr_b32 s22, s21, 8
	s_lshr_b32 s21, s21, 6
	s_lshl_b32 s21, s21, 10
	s_barrier
	s_mov_b32 m0, s21
	s_nop 0
	global_load_lds_dwordx4 v1, s[36:37]
	s_add_i32 m0, s21, 0x2000
	s_nop 0
	global_load_lds_dwordx4 v1, s[36:37]
	s_add_i32 m0, s21, 0x4000
	s_nop 0
	global_load_lds_dwordx4 v1, s[36:37]
	s_add_i32 m0, s21, 0x6000
	s_nop 0
	global_load_lds_dwordx4 v1, s[36:37]
	s_add_i32 m0, s21, 0x8000
	s_nop 0
	global_load_lds_dwordx4 v1, s[38:39]
	s_add_i32 m0, s21, 0xa000
	s_add_u32 s40, s38, 0x58000
	s_addc_u32 s41, s39, 0
	global_load_lds_dwordx4 v1, s[40:41]
	s_add_i32 m0, s21, 0xc000
	s_add_u32 s40, s38, 0xb0000
	s_addc_u32 s41, s39, 0
	global_load_lds_dwordx4 v1, s[40:41]
	s_add_i32 m0, s21, 0xe000
	s_add_u32 s40, s38, 0x108000
	s_addc_u32 s41, s39, 0
	global_load_lds_dwordx4 v1, s[40:41]
	s_add_i32 m0, s21, 0x10000
	s_add_u32 s40, s36, 0x80
	s_addc_u32 s41, s37, 0
	global_load_lds_dwordx4 v1, s[40:41]
	s_add_i32 m0, s21, 0x18000
	s_add_u32 s40, s38, 0x80
	s_addc_u32 s41, s39, 0
	global_load_lds_dwordx4 v1, s[40:41]
	s_waitcnt vmcnt(2)
	s_barrier
	s_cmp_eq_u32 s22, 0
	s_cbranch_scc1 .Lp5t_skew0
	s_barrier
.Lp5t_skew0:
	ds_read_b128 v[130:133], v200 offset:0
	ds_read_b128 v[134:137], v200 offset:2048
	ds_read_b128 v[162:165], v202 offset:32768
	ds_read_b128 v[166:169], v202 offset:34816
	ds_read_b128 v[170:173], v202 offset:36864
	ds_read_b128 v[174:177], v202 offset:38912
	s_add_i32 m0, s21, 0x14000
	s_add_u32 s40, s36, 0x80
	s_addc_u32 s41, s37, 0
	global_load_lds_dwordx4 v1, s[40:41]
	s_add_i32 m0, s21, 0x1a000
	s_add_u32 s40, s38, 0x58080
	s_addc_u32 s41, s39, 0
	global_load_lds_dwordx4 v1, s[40:41]
	s_waitcnt lgkmcnt(0)
	s_barrier
	v_mfma_f32_16x16x32_f16 v[126:129], v[162:165], v[130:133], 0
	v_mfma_f32_16x16x32_f16 v[122:125], v[166:169], v[130:133], 0
	v_mfma_f32_16x16x32_f16 v[118:121], v[170:173], v[130:133], 0
	v_mfma_f32_16x16x32_f16 v[114:117], v[174:177], v[130:133], 0
	v_mfma_f32_16x16x32_f16 v[110:113], v[162:165], v[134:137], 0
	v_mfma_f32_16x16x32_f16 v[106:109], v[166:169], v[134:137], 0
	v_mfma_f32_16x16x32_f16 v[102:105], v[170:173], v[134:137], 0
	v_mfma_f32_16x16x32_f16 v[98:101], v[174:177], v[134:137], 0
	s_barrier
	s_add_i32 m0, s21, 0x1c000
	s_add_u32 s40, s38, 0xb0080
	s_addc_u32 s41, s39, 0
	global_load_lds_dwordx4 v1, s[40:41]
	s_add_i32 m0, s21, 0x1e000
	s_add_u32 s40, s38, 0x108080
	s_addc_u32 s41, s39, 0
	global_load_lds_dwordx4 v1, s[40:41]
	s_waitcnt lgkmcnt(0)
	s_barrier
	s_barrier
	ds_read_b128 v[130:133], v201 offset:0
	ds_read_b128 v[134:137], v201 offset:2048
	ds_read_b128 v[162:165], v203 offset:32768
	ds_read_b128 v[166:169], v203 offset:34816
	ds_read_b128 v[170:173], v203 offset:36864
	ds_read_b128 v[174:177], v203 offset:38912
	s_add_i32 m0, s21, 0x12000
	s_add_u32 s40, s36, 0x80
	s_addc_u32 s41, s37, 0
	global_load_lds_dwordx4 v1, s[40:41]
	s_add_i32 m0, s21, 0x16000
	s_add_u32 s40, s36, 0x80
	s_addc_u32 s41, s37, 0
	global_load_lds_dwordx4 v1, s[40:41]
	s_waitcnt lgkmcnt(0)
	s_barrier
	v_mfma_f32_16x16x32_f16 v[126:129], v[162:165], v[130:133], v[126:129]
	v_mfma_f32_16x16x32_f16 v[122:125], v[166:169], v[130:133], v[122:125]
	v_mfma_f32_16x16x32_f16 v[118:121], v[170:173], v[130:133], v[118:121]
	v_mfma_f32_16x16x32_f16 v[114:117], v[174:177], v[130:133], v[114:117]
	v_mfma_f32_16x16x32_f16 v[110:113], v[162:165], v[134:137], v[110:113]
	v_mfma_f32_16x16x32_f16 v[106:109], v[166:169], v[134:137], v[106:109]
	v_mfma_f32_16x16x32_f16 v[102:105], v[170:173], v[134:137], v[102:105]
	v_mfma_f32_16x16x32_f16 v[98:101], v[174:177], v[134:137], v[98:101]
	s_barrier
	s_mov_b32 m0, s21
	s_add_u32 s40, s36, 0x100
	s_addc_u32 s41, s37, 0
	global_load_lds_dwordx4 v1, s[40:41]
	s_add_i32 m0, s21, 0x8000
	s_add_u32 s40, s38, 0x100
	s_addc_u32 s41, s39, 0
	global_load_lds_dwordx4 v1, s[40:41]
	s_waitcnt vmcnt(4) lgkmcnt(0)
	s_barrier
	s_barrier
	s_add_u32 s36, s36, 0x80
	s_addc_u32 s37, s37, 0
	s_add_u32 s38, s38, 0x80
	s_addc_u32 s39, s39, 0
	ds_read_b128 v[130:133], v204 offset:0
	ds_read_b128 v[134:137], v204 offset:2048
	ds_read_b128 v[162:165], v206 offset:32768
	ds_read_b128 v[166:169], v206 offset:34816
	ds_read_b128 v[170:173], v206 offset:36864
	ds_read_b128 v[174:177], v206 offset:38912
	s_add_i32 m0, s21, 0x4000
	s_add_u32 s40, s36, 0x80
	s_addc_u32 s41, s37, 0
	global_load_lds_dwordx4 v1, s[40:41]
	s_add_i32 m0, s21, 0xa000
	s_add_u32 s40, s38, 0x58080
	s_addc_u32 s41, s39, 0
	global_load_lds_dwordx4 v1, s[40:41]
	s_waitcnt vmcnt(4) lgkmcnt(0)
	s_barrier
	v_mfma_f32_16x16x32_f16 v[126:129], v[162:165], v[130:133], v[126:129]
	v_mfma_f32_16x16x32_f16 v[122:125], v[166:169], v[130:133], v[122:125]
	v_mfma_f32_16x16x32_f16 v[118:121], v[170:173], v[130:133], v[118:121]
	v_mfma_f32_16x16x32_f16 v[114:117], v[174:177], v[130:133], v[114:117]
	v_mfma_f32_16x16x32_f16 v[110:113], v[162:165], v[134:137], v[110:113]
	v_mfma_f32_16x16x32_f16 v[106:109], v[166:169], v[134:137], v[106:109]
	v_mfma_f32_16x16x32_f16 v[102:105], v[170:173], v[134:137], v[102:105]
	v_mfma_f32_16x16x32_f16 v[98:101], v[174:177], v[134:137], v[98:101]
	s_barrier
	s_add_i32 m0, s21, 0xc000
	s_add_u32 s40, s38, 0xb0080
	s_addc_u32 s41, s39, 0
	global_load_lds_dwordx4 v1, s[40:41]
	s_add_i32 m0, s21, 0xe000
	s_add_u32 s40, s38, 0x108080
	s_addc_u32 s41, s39, 0
	global_load_lds_dwordx4 v1, s[40:41]
	s_waitcnt lgkmcnt(0)
	s_barrier
	s_barrier
	ds_read_b128 v[130:133], v205 offset:0
	ds_read_b128 v[134:137], v205 offset:2048
	ds_read_b128 v[162:165], v207 offset:32768
	ds_read_b128 v[166:169], v207 offset:34816
	ds_read_b128 v[170:173], v207 offset:36864
	ds_read_b128 v[174:177], v207 offset:38912
	s_add_i32 m0, s21, 0x2000
	s_add_u32 s40, s36, 0x80
	s_addc_u32 s41, s37, 0
	global_load_lds_dwordx4 v1, s[40:41]
	s_add_i32 m0, s21, 0x6000
	s_add_u32 s40, s36, 0x80
	s_addc_u32 s41, s37, 0
	global_load_lds_dwordx4 v1, s[40:41]
	s_waitcnt lgkmcnt(0)
	s_barrier
	v_mfma_f32_16x16x32_f16 v[126:129], v[162:165], v[130:133], v[126:129]
	v_mfma_f32_16x16x32_f16 v[122:125], v[166:169], v[130:133], v[122:125]
	v_mfma_f32_16x16x32_f16 v[118:121], v[170:173], v[130:133], v[118:121]
	v_mfma_f32_16x16x32_f16 v[114:117], v[174:177], v[130:133], v[114:117]
	v_mfma_f32_16x16x32_f16 v[110:113], v[162:165], v[134:137], v[110:113]
	v_mfma_f32_16x16x32_f16 v[106:109], v[166:169], v[134:137], v[106:109]
	v_mfma_f32_16x16x32_f16 v[102:105], v[170:173], v[134:137], v[102:105]
	v_mfma_f32_16x16x32_f16 v[98:101], v[174:177], v[134:137], v[98:101]
	s_barrier
	s_add_i32 m0, s21, 0x10000
	s_add_u32 s40, s36, 0x100
	s_addc_u32 s41, s37, 0
	global_load_lds_dwordx4 v1, s[40:41]
	s_add_i32 m0, s21, 0x18000
	s_add_u32 s40, s38, 0x100
	s_addc_u32 s41, s39, 0
	global_load_lds_dwordx4 v1, s[40:41]
	s_waitcnt vmcnt(4) lgkmcnt(0)
	s_barrier
	s_barrier
	s_add_u32 s36, s36, 0x80
	s_addc_u32 s37, s37, 0
	s_add_u32 s38, s38, 0x80
	s_addc_u32 s39, s39, 0
	s_movk_i32 s23, 20
.Lp5t_loop:
	ds_read_b128 v[130:133], v200 offset:0
	ds_read_b128 v[134:137], v200 offset:2048
	ds_read_b128 v[162:165], v202 offset:32768
	ds_read_b128 v[166:169], v202 offset:34816
	ds_read_b128 v[170:173], v202 offset:36864
	ds_read_b128 v[174:177], v202 offset:38912
	s_add_i32 m0, s21, 0x14000
	s_add_u32 s40, s36, 0x80
	s_addc_u32 s41, s37, 0
	global_load_lds_dwordx4 v1, s[40:41]
	s_add_i32 m0, s21, 0x1a000
	s_add_u32 s40, s38, 0x58080
	s_addc_u32 s41, s39, 0
	global_load_lds_dwordx4 v1, s[40:41]
	s_waitcnt vmcnt(4) lgkmcnt(0)
	s_barrier
	v_mfma_f32_16x16x32_f16 v[126:129], v[162:165], v[130:133], v[126:129]
	v_mfma_f32_16x16x32_f16 v[122:125], v[166:169], v[130:133], v[122:125]
	v_mfma_f32_16x16x32_f16 v[118:121], v[170:173], v[130:133], v[118:121]
	v_mfma_f32_16x16x32_f16 v[114:117], v[174:177], v[130:133], v[114:117]
	v_mfma_f32_16x16x32_f16 v[110:113], v[162:165], v[134:137], v[110:113]
	v_mfma_f32_16x16x32_f16 v[106:109], v[166:169], v[134:137], v[106:109]
	v_mfma_f32_16x16x32_f16 v[102:105], v[170:173], v[134:137], v[102:105]
	v_mfma_f32_16x16x32_f16 v[98:101], v[174:177], v[134:137], v[98:101]
	s_barrier
	s_add_i32 m0, s21, 0x1c000
	s_add_u32 s40, s38, 0xb0080
	s_addc_u32 s41, s39, 0
	global_load_lds_dwordx4 v1, s[40:41]
	s_add_i32 m0, s21, 0x1e000
	s_add_u32 s40, s38, 0x108080
	s_addc_u32 s41, s39, 0
	global_load_lds_dwordx4 v1, s[40:41]
	s_waitcnt lgkmcnt(0)
	s_barrier
	s_barrier
	ds_read_b128 v[130:133], v201 offset:0
	ds_read_b128 v[134:137], v201 offset:2048
	ds_read_b128 v[162:165], v203 offset:32768
	ds_read_b128 v[166:169], v203 offset:34816
	ds_read_b128 v[170:173], v203 offset:36864
	ds_read_b128 v[174:177], v203 offset:38912
	s_add_i32 m0, s21, 0x12000
	s_add_u32 s40, s36, 0x80
	s_addc_u32 s41, s37, 0
	global_load_lds_dwordx4 v1, s[40:41]
	s_add_i32 m0, s21, 0x16000
	s_add_u32 s40, s36, 0x80
	s_addc_u32 s41, s37, 0
	global_load_lds_dwordx4 v1, s[40:41]
	s_waitcnt lgkmcnt(0)
	s_barrier
	v_mfma_f32_16x16x32_f16 v[126:129], v[162:165], v[130:133], v[126:129]
	v_mfma_f32_16x16x32_f16 v[122:125], v[166:169], v[130:133], v[122:125]
	v_mfma_f32_16x16x32_f16 v[118:121], v[170:173], v[130:133], v[118:121]
	v_mfma_f32_16x16x32_f16 v[114:117], v[174:177], v[130:133], v[114:117]
	v_mfma_f32_16x16x32_f16 v[110:113], v[162:165], v[134:137], v[110:113]
	v_mfma_f32_16x16x32_f16 v[106:109], v[166:169], v[134:137], v[106:109]
	v_mfma_f32_16x16x32_f16 v[102:105], v[170:173], v[134:137], v[102:105]
	v_mfma_f32_16x16x32_f16 v[98:101], v[174:177], v[134:137], v[98:101]
	s_barrier
	s_mov_b32 m0, s21
	s_add_u32 s40, s36, 0x100
	s_addc_u32 s41, s37, 0
	global_load_lds_dwordx4 v1, s[40:41]
	s_add_i32 m0, s21, 0x8000
	s_add_u32 s40, s38, 0x100
	s_addc_u32 s41, s39, 0
	global_load_lds_dwordx4 v1, s[40:41]
	s_waitcnt vmcnt(4) lgkmcnt(0)
	s_barrier
	s_barrier
	s_add_u32 s36, s36, 0x80
	s_addc_u32 s37, s37, 0
	s_add_u32 s38, s38, 0x80
	s_addc_u32 s39, s39, 0
	ds_read_b128 v[130:133], v204 offset:0
	ds_read_b128 v[134:137], v204 offset:2048
	ds_read_b128 v[162:165], v206 offset:32768
	ds_read_b128 v[166:169], v206 offset:34816
	ds_read_b128 v[170:173], v206 offset:36864
	ds_read_b128 v[174:177], v206 offset:38912
	s_add_i32 m0, s21, 0x4000
	s_add_u32 s40, s36, 0x80
	s_addc_u32 s41, s37, 0
	global_load_lds_dwordx4 v1, s[40:41]
	s_add_i32 m0, s21, 0xa000
	s_add_u32 s40, s38, 0x58080
	s_addc_u32 s41, s39, 0
	global_load_lds_dwordx4 v1, s[40:41]
	s_waitcnt vmcnt(4) lgkmcnt(0)
	s_barrier
	v_mfma_f32_16x16x32_f16 v[126:129], v[162:165], v[130:133], v[126:129]
	v_mfma_f32_16x16x32_f16 v[122:125], v[166:169], v[130:133], v[122:125]
	v_mfma_f32_16x16x32_f16 v[118:121], v[170:173], v[130:133], v[118:121]
	v_mfma_f32_16x16x32_f16 v[114:117], v[174:177], v[130:133], v[114:117]
	v_mfma_f32_16x16x32_f16 v[110:113], v[162:165], v[134:137], v[110:113]
	v_mfma_f32_16x16x32_f16 v[106:109], v[166:169], v[134:137], v[106:109]
	v_mfma_f32_16x16x32_f16 v[102:105], v[170:173], v[134:137], v[102:105]
	v_mfma_f32_16x16x32_f16 v[98:101], v[174:177], v[134:137], v[98:101]
	s_barrier
	s_add_i32 m0, s21, 0xc000
	s_add_u32 s40, s38, 0xb0080
	s_addc_u32 s41, s39, 0
	global_load_lds_dwordx4 v1, s[40:41]
	s_add_i32 m0, s21, 0xe000
	s_add_u32 s40, s38, 0x108080
	s_addc_u32 s41, s39, 0
	global_load_lds_dwordx4 v1, s[40:41]
	s_waitcnt lgkmcnt(0)
	s_barrier
	s_barrier
	ds_read_b128 v[130:133], v205 offset:0
	ds_read_b128 v[134:137], v205 offset:2048
	ds_read_b128 v[162:165], v207 offset:32768
	ds_read_b128 v[166:169], v207 offset:34816
	ds_read_b128 v[170:173], v207 offset:36864
	ds_read_b128 v[174:177], v207 offset:38912
	s_add_i32 m0, s21, 0x2000
	s_add_u32 s40, s36, 0x80
	s_addc_u32 s41, s37, 0
	global_load_lds_dwordx4 v1, s[40:41]
	s_add_i32 m0, s21, 0x6000
	s_add_u32 s40, s36, 0x80
	s_addc_u32 s41, s37, 0
	global_load_lds_dwordx4 v1, s[40:41]
	s_waitcnt lgkmcnt(0)
	s_barrier
	v_mfma_f32_16x16x32_f16 v[126:129], v[162:165], v[130:133], v[126:129]
	v_mfma_f32_16x16x32_f16 v[122:125], v[166:169], v[130:133], v[122:125]
	v_mfma_f32_16x16x32_f16 v[118:121], v[170:173], v[130:133], v[118:121]
	v_mfma_f32_16x16x32_f16 v[114:117], v[174:177], v[130:133], v[114:117]
	v_mfma_f32_16x16x32_f16 v[110:113], v[162:165], v[134:137], v[110:113]
	v_mfma_f32_16x16x32_f16 v[106:109], v[166:169], v[134:137], v[106:109]
	v_mfma_f32_16x16x32_f16 v[102:105], v[170:173], v[134:137], v[102:105]
	v_mfma_f32_16x16x32_f16 v[98:101], v[174:177], v[134:137], v[98:101]
	s_barrier
	s_add_i32 m0, s21, 0x10000
	s_add_u32 s40, s36, 0x100
	s_addc_u32 s41, s37, 0
	global_load_lds_dwordx4 v1, s[40:41]
	s_add_i32 m0, s21, 0x18000
	s_add_u32 s40, s38, 0x100
	s_addc_u32 s41, s39, 0
	global_load_lds_dwordx4 v1, s[40:41]
	s_waitcnt vmcnt(4) lgkmcnt(0)
	s_barrier
	s_barrier
	s_add_u32 s36, s36, 0x80
	s_addc_u32 s37, s37, 0
	s_add_u32 s38, s38, 0x80
	s_addc_u32 s39, s39, 0
	s_add_i32 s23, s23, -1
	s_cmp_lg_u32 s23, 0
	s_cbranch_scc1 .Lp5t_loop
	ds_read_b128 v[130:133], v200 offset:0
	ds_read_b128 v[134:137], v200 offset:2048
	ds_read_b128 v[162:165], v202 offset:32768
	ds_read_b128 v[166:169], v202 offset:34816
	ds_read_b128 v[170:173], v202 offset:36864
	ds_read_b128 v[174:177], v202 offset:38912
	s_add_i32 m0, s21, 0x14000
	s_add_u32 s40, s36, 0x80
	s_addc_u32 s41, s37, 0
	global_load_lds_dwordx4 v1, s[40:41]
	s_add_i32 m0, s21, 0x1a000
	s_add_u32 s40, s38, 0x58080
	s_addc_u32 s41, s39, 0
	global_load_lds_dwordx4 v1, s[40:41]
	s_waitcnt vmcnt(4) lgkmcnt(0)
	s_barrier
	v_mfma_f32_16x16x32_f16 v[126:129], v[162:165], v[130:133], v[126:129]
	v_mfma_f32_16x16x32_f16 v[122:125], v[166:169], v[130:133], v[122:125]
	v_mfma_f32_16x16x32_f16 v[118:121], v[170:173], v[130:133], v[118:121]
	v_mfma_f32_16x16x32_f16 v[114:117], v[174:177], v[130:133], v[114:117]
	v_mfma_f32_16x16x32_f16 v[110:113], v[162:165], v[134:137], v[110:113]
	v_mfma_f32_16x16x32_f16 v[106:109], v[166:169], v[134:137], v[106:109]
	v_mfma_f32_16x16x32_f16 v[102:105], v[170:173], v[134:137], v[102:105]
	v_mfma_f32_16x16x32_f16 v[98:101], v[174:177], v[134:137], v[98:101]
	s_barrier
	s_add_i32 m0, s21, 0x1c000
	s_add_u32 s40, s38, 0xb0080
	s_addc_u32 s41, s39, 0
	global_load_lds_dwordx4 v1, s[40:41]
	s_add_i32 m0, s21, 0x1e000
	s_add_u32 s40, s38, 0x108080
	s_addc_u32 s41, s39, 0
	global_load_lds_dwordx4 v1, s[40:41]
	s_waitcnt lgkmcnt(0)
	s_barrier
	s_barrier
	ds_read_b128 v[130:133], v201 offset:0
	ds_read_b128 v[134:137], v201 offset:2048
	ds_read_b128 v[162:165], v203 offset:32768
	ds_read_b128 v[166:169], v203 offset:34816
	ds_read_b128 v[170:173], v203 offset:36864
	ds_read_b128 v[174:177], v203 offset:38912
	s_add_i32 m0, s21, 0x12000
	s_add_u32 s40, s36, 0x80
	s_addc_u32 s41, s37, 0
	global_load_lds_dwordx4 v1, s[40:41]
	s_add_i32 m0, s21, 0x16000
	s_add_u32 s40, s36, 0x80
	s_addc_u32 s41, s37, 0
	global_load_lds_dwordx4 v1, s[40:41]
	s_waitcnt lgkmcnt(0)
	s_barrier
	v_mfma_f32_16x16x32_f16 v[126:129], v[162:165], v[130:133], v[126:129]
	v_mfma_f32_16x16x32_f16 v[122:125], v[166:169], v[130:133], v[122:125]
	v_mfma_f32_16x16x32_f16 v[118:121], v[170:173], v[130:133], v[118:121]
	v_mfma_f32_16x16x32_f16 v[114:117], v[174:177], v[130:133], v[114:117]
	v_mfma_f32_16x16x32_f16 v[110:113], v[162:165], v[134:137], v[110:113]
	v_mfma_f32_16x16x32_f16 v[106:109], v[166:169], v[134:137], v[106:109]
	v_mfma_f32_16x16x32_f16 v[102:105], v[170:173], v[134:137], v[102:105]
	v_mfma_f32_16x16x32_f16 v[98:101], v[174:177], v[134:137], v[98:101]
	s_barrier
	s_waitcnt vmcnt(2) lgkmcnt(0)
	s_barrier
	s_barrier
	s_add_u32 s36, s36, 0x80
	s_addc_u32 s37, s37, 0
	s_add_u32 s38, s38, 0x80
	s_addc_u32 s39, s39, 0
	ds_read_b128 v[130:133], v204 offset:0
	ds_read_b128 v[134:137], v204 offset:2048
	ds_read_b128 v[162:165], v206 offset:32768
	ds_read_b128 v[166:169], v206 offset:34816
	ds_read_b128 v[170:173], v206 offset:36864
	ds_read_b128 v[174:177], v206 offset:38912
	s_waitcnt vmcnt(0) lgkmcnt(0)
	s_barrier
	v_mfma_f32_16x16x32_f16 v[126:129], v[162:165], v[130:133], v[126:129]
	v_mfma_f32_16x16x32_f16 v[122:125], v[166:169], v[130:133], v[122:125]
	v_mfma_f32_16x16x32_f16 v[118:121], v[170:173], v[130:133], v[118:121]
	v_mfma_f32_16x16x32_f16 v[114:117], v[174:177], v[130:133], v[114:117]
	v_mfma_f32_16x16x32_f16 v[110:113], v[162:165], v[134:137], v[110:113]
	v_mfma_f32_16x16x32_f16 v[106:109], v[166:169], v[134:137], v[106:109]
	v_mfma_f32_16x16x32_f16 v[102:105], v[170:173], v[134:137], v[102:105]
	v_mfma_f32_16x16x32_f16 v[98:101], v[174:177], v[134:137], v[98:101]
	s_barrier
	s_waitcnt lgkmcnt(0)
	s_barrier
	s_barrier
	ds_read_b128 v[130:133], v205 offset:0
	ds_read_b128 v[134:137], v205 offset:2048
	ds_read_b128 v[162:165], v207 offset:32768
	ds_read_b128 v[166:169], v207 offset:34816
	ds_read_b128 v[170:173], v207 offset:36864
	ds_read_b128 v[174:177], v207 offset:38912
	s_waitcnt lgkmcnt(0)
	s_barrier
	v_mfma_f32_16x16x32_f16 v[126:129], v[162:165], v[130:133], v[126:129]
	v_mfma_f32_16x16x32_f16 v[122:125], v[166:169], v[130:133], v[122:125]
	v_mfma_f32_16x16x32_f16 v[118:121], v[170:173], v[130:133], v[118:121]
	v_mfma_f32_16x16x32_f16 v[114:117], v[174:177], v[130:133], v[114:117]
	v_mfma_f32_16x16x32_f16 v[110:113], v[162:165], v[134:137], v[110:113]
	v_mfma_f32_16x16x32_f16 v[106:109], v[166:169], v[134:137], v[106:109]
	v_mfma_f32_16x16x32_f16 v[102:105], v[170:173], v[134:137], v[102:105]
	v_mfma_f32_16x16x32_f16 v[98:101], v[174:177], v[134:137], v[98:101]
	s_barrier
	s_waitcnt lgkmcnt(0)
	s_barrier
	s_barrier
	s_cmp_eq_u32 s22, 1
	s_cbranch_scc1 .Lp5t_skew1
	s_barrier
.Lp5t_skew1:
	s_nop 7
	s_nop 1
	s_cmp_lt_u32 s20, 0x80
	v_readlane_b32 s2, v254, 12
	v_readlane_b32 s3, v254, 13
	v_readlane_b32 s4, v254, 55
	v_readlane_b32 s5, v254, 56
	s_cselect_b32 s42, s2, s4
	s_cselect_b32 s43, s3, s5
	s_and_b32 s2, s20, 0x7f
	s_lshl_b32 s2, s2, 20
	s_lshl_b32 s3, s19, 10
	s_add_i32 s2, s2, s3
	s_add_i32 s2, s2, s28
	s_add_u32 s42, s42, s2
	s_addc_u32 s43, s43, 0
	s_lshr_b32 s2, s20, 3
	s_cmp_lt_u32 s20, 0x80
	s_cselect_b32 s2, s2, 16
	s_add_i32 s2, s2, s54
	s_mul_i32 s2, s2, 0x6000
	s_add_i32 s2, s2, s3
	s_add_i32 s2, s2, 0x5000
	v_readlane_b32 s4, v254, 14
	v_readlane_b32 s5, v254, 15
	s_nop 3
	s_add_u32 s44, s4, s2
	s_addc_u32 s45, s5, 0
	v_and_b32_e32 v197, 15, v222
	v_lshrrev_b32_e32 v198, 8, v222
	v_lshl_or_b32 v197, v198, 5, v197
	v_bfe_u32 v198, v222, 6, 2
	v_bfe_u32 v199, v222, 4, 2
	v_lshlrev_b32_e32 v199, 4, v199
	v_lshl_or_b32 v196, v198, 8, v199
	v_lshl_or_b32 v194, v197, 12, v196
	s_nop 1
	global_load_dwordx4 v[178:181], v196, s[44:45] offset:0
	global_load_dwordx4 v[182:185], v196, s[44:45] offset:64
	global_load_dwordx4 v[186:189], v196, s[44:45] offset:128
	global_load_dwordx4 v[190:193], v196, s[44:45] offset:192
	global_load_dwordx4 v[130:133], v194, s[42:43] offset:0
	global_load_dwordx4 v[134:137], v194, s[42:43] offset:64
	global_load_dwordx4 v[138:141], v194, s[42:43] offset:128
	global_load_dwordx4 v[142:145], v194, s[42:43] offset:192
	v_add_u32_e32 v195, 0x10000, v194
	global_load_dwordx4 v[146:149], v195, s[42:43] offset:0
	global_load_dwordx4 v[150:153], v195, s[42:43] offset:64
	global_load_dwordx4 v[154:157], v195, s[42:43] offset:128
	global_load_dwordx4 v[158:161], v195, s[42:43] offset:192
	s_waitcnt vmcnt(0)
	v_pk_fma_f32 v[126:127], v[126:127], v[178:179], v[130:131]
	v_pk_fma_f32 v[128:129], v[128:129], v[180:181], v[132:133]
	v_pk_fma_f32 v[122:123], v[122:123], v[182:183], v[134:135]
	v_pk_fma_f32 v[124:125], v[124:125], v[184:185], v[136:137]
	v_pk_fma_f32 v[118:119], v[118:119], v[186:187], v[138:139]
	v_pk_fma_f32 v[120:121], v[120:121], v[188:189], v[140:141]
	v_pk_fma_f32 v[114:115], v[114:115], v[190:191], v[142:143]
	v_pk_fma_f32 v[116:117], v[116:117], v[192:193], v[144:145]
	global_store_dwordx4 v194, v[126:129], s[42:43] offset:0
	global_store_dwordx4 v194, v[122:125], s[42:43] offset:64
	global_store_dwordx4 v194, v[118:121], s[42:43] offset:128
	global_store_dwordx4 v194, v[114:117], s[42:43] offset:192
	v_pk_fma_f32 v[110:111], v[110:111], v[178:179], v[146:147]
	v_pk_fma_f32 v[112:113], v[112:113], v[180:181], v[148:149]
	v_pk_fma_f32 v[106:107], v[106:107], v[182:183], v[150:151]
	v_pk_fma_f32 v[108:109], v[108:109], v[184:185], v[152:153]
	v_pk_fma_f32 v[102:103], v[102:103], v[186:187], v[154:155]
	v_pk_fma_f32 v[104:105], v[104:105], v[188:189], v[156:157]
	v_pk_fma_f32 v[98:99], v[98:99], v[190:191], v[158:159]
	v_pk_fma_f32 v[100:101], v[100:101], v[192:193], v[160:161]
	global_store_dwordx4 v195, v[110:113], s[42:43] offset:0
	global_store_dwordx4 v195, v[106:109], s[42:43] offset:64
	global_store_dwordx4 v195, v[102:105], s[42:43] offset:128
	global_store_dwordx4 v195, v[98:101], s[42:43] offset:192
	s_waitcnt vmcnt(0)
.Lp5t_none:
	v_readlane_b32 s36, v254, 0
	v_readlane_b32 s37, v254, 1
	v_readlane_b32 s38, v254, 2
	v_readlane_b32 s39, v254, 3
	v_readlane_b32 s40, v254, 4
	v_readlane_b32 s41, v254, 5
	v_readlane_b32 s42, v254, 6
	v_readlane_b32 s43, v254, 7
	v_readlane_b32 s44, v254, 8
	v_readlane_b32 s45, v254, 9
	v_readlane_b32 s46, v254, 10
	v_readlane_b32 s47, v254, 11
	v_readlane_b32 s48, v254, 12
	v_readlane_b32 s49, v254, 13
	v_readlane_b32 s50, v254, 14
	v_readlane_b32 s51, v254, 15
	s_mov_b64 s[12:13], s[48:49]
	s_mov_b64 s[14:15], s[50:51]
	s_mov_b64 s[2:3], 0x5000
	s_add_i32 s18, s18, s95
	s_branch .LBB0_1177
